# normM/norm2: second row's gain/scale/shift loads issued in the same batch as the first row's (one L2 round trip per iteration)
# speedup vs baseline: 1.0048x; 1.0048x over previous
.LBB0_979:
	s_or_b64 exec, exec, s[44:45]
	s_waitcnt vmcnt(0) lgkmcnt(0)
	v_mul_f32_e32 v52, v29, v29
	v_mul_f32_e32 v53, v25, v25
	v_fmac_f32_e32 v52, v28, v28
	v_fmac_f32_e32 v53, v24, v24
	v_fmac_f32_e32 v52, v30, v30
	v_fmac_f32_e32 v53, v26, v26
	v_fmac_f32_e32 v52, v31, v31
	v_fmac_f32_e32 v53, v27, v27
	v_add_f32_e32 v52, v53, v52
	v_mul_f32_e32 v53, v17, v17
	v_fmac_f32_e32 v53, v16, v16
	v_fmac_f32_e32 v53, v18, v18
	v_fmac_f32_e32 v53, v19, v19
	v_add_f32_e32 v52, v53, v52
	v_mul_f32_e32 v53, v21, v21
	v_fmac_f32_e32 v53, v20, v20
	v_fmac_f32_e32 v53, v22, v22
	v_fmac_f32_e32 v53, v23, v23
	v_add_f32_e32 v52, v53, v52
	v_mul_f32_e32 v53, v13, v13
	v_mul_f32_e32 v54, v9, v9
	v_fmac_f32_e32 v53, v12, v12
	v_fmac_f32_e32 v54, v8, v8
	v_fmac_f32_e32 v53, v14, v14
	v_fmac_f32_e32 v54, v10, v10
	v_fmac_f32_e32 v53, v15, v15
	v_fmac_f32_e32 v54, v11, v11
	v_add_f32_e32 v53, v54, v53
	v_mul_f32_e32 v54, v1, v1
	v_fmac_f32_e32 v54, v0, v0
	v_fmac_f32_e32 v54, v2, v2
	v_fmac_f32_e32 v54, v3, v3
	v_add_f32_e32 v53, v54, v53
	v_mul_f32_e32 v54, v5, v5
	v_fmac_f32_e32 v54, v4, v4
	v_fmac_f32_e32 v54, v6, v6
	v_fmac_f32_e32 v54, v7, v7
	v_add_f32_e32 v53, v54, v53
	ds_bpermute_b32 v54, v35, v52
	s_mov_b32 s30, 0x800000
	s_mov_b64 s[42:43], 0x4000
	global_load_dwordx4 v[68:71], v[38:39], off offset:16
	global_load_dwordx4 v[72:75], v[38:39], off
	s_waitcnt lgkmcnt(0)
	v_add_f32_e32 v52, v52, v54
	ds_bpermute_b32 v54, v35, v53
	s_waitcnt lgkmcnt(0)
	v_add_f32_e32 v53, v53, v54
	ds_bpermute_b32 v54, v62, v52
	s_waitcnt lgkmcnt(0)
	v_add_f32_e32 v52, v52, v54
	ds_bpermute_b32 v54, v62, v53
	s_waitcnt lgkmcnt(0)
	v_add_f32_e32 v53, v53, v54
	ds_bpermute_b32 v54, v63, v52
	s_waitcnt lgkmcnt(0)
	v_add_f32_e32 v52, v52, v54
	ds_bpermute_b32 v54, v63, v53
	s_waitcnt lgkmcnt(0)
	v_add_f32_e32 v53, v53, v54
	ds_bpermute_b32 v54, v64, v52
	s_waitcnt lgkmcnt(0)
	v_add_f32_e32 v52, v52, v54
	ds_bpermute_b32 v54, v64, v53
	s_waitcnt lgkmcnt(0)
	v_add_f32_e32 v53, v53, v54
	ds_bpermute_b32 v54, v65, v52
	s_waitcnt lgkmcnt(0)
	v_add_f32_e32 v52, v52, v54
	ds_bpermute_b32 v54, v65, v53
	s_waitcnt lgkmcnt(0)
	v_add_f32_e32 v53, v53, v54
	ds_bpermute_b32 v54, v66, v52
	ds_bpermute_b32 v58, v66, v53
	s_waitcnt lgkmcnt(1)
	v_add_f32_e32 v52, v52, v54
	v_fmamk_f32 v52, v52, 0x3a800000, v191
	v_cmp_gt_f32_e32 vcc, s30, v52
	v_mul_f32_e32 v56, 0x4b800000, v52
	v_min_i32_e32 v54, 0x8000, v32
	v_cndmask_b32_e32 v52, v52, v56, vcc
	v_ashrrev_i32_e32 v54, 12, v54
	v_rsq_f32_e32 v52, v52
	v_mul_i32_i24_e32 v54, 9, v54
	v_ashrrev_i32_e32 v55, 31, v54
	v_lshlrev_b64 v[54:55], 12, v[54:55]
	v_mul_f32_e32 v56, 0x45800000, v52
	v_lshl_add_u64 v[60:61], v[42:43], 0, v[54:55]
	s_movk_i32 s30, 0x4000
	v_cndmask_b32_e32 v52, v52, v56, vcc
	v_add_co_u32_e32 v76, vcc, s30, v60
	v_lshl_add_u64 v[56:57], v[60:61], 0, s[42:43]
	s_mov_b64 s[42:43], 0x3000
	v_addc_co_u32_e32 v77, vcc, 0, v61, vcc
	s_movk_i32 s30, 0x3000
	v_lshl_add_u64 v[54:55], v[60:61], 0, s[42:43]
	v_add_co_u32_e32 v60, vcc, s30, v60
	flat_load_dwordx4 v[76:79], v[76:77]
	s_nop 0
	v_addc_co_u32_e32 v61, vcc, 0, v61, vcc
	flat_load_dwordx4 v[80:83], v[60:61]
	global_load_dwordx4 v[112:115], v[56:57], off offset:16
	global_load_dwordx4 v[116:119], v[54:55], off offset:16
	global_load_dwordx4 v[120:123], v[40:41], off offset:16
	global_load_dwordx4 v[124:127], v[40:41], off
	global_load_dwordx4 v[128:131], v[56:57], off offset:2048
	global_load_dwordx4 v[132:135], v[54:55], off offset:2048
	global_load_dwordx4 v[136:139], v[56:57], off offset:2064
	global_load_dwordx4 v[140:143], v[54:55], off offset:2064
	v_min_i32_e32 v104, 0x8000, v33
	v_ashrrev_i32_e32 v104, 12, v104
	v_mul_i32_i24_e32 v104, 9, v104
	v_ashrrev_i32_e32 v105, 31, v104
	v_lshlrev_b64 v[104:105], 12, v[104:105]
	v_lshl_add_u64 v[104:105], v[42:43], 0, v[104:105]
	s_mov_b64 s[98:99], 0x4000
	v_lshl_add_u64 v[106:107], v[104:105], 0, s[98:99]
	s_mov_b64 s[98:99], 0x3000
	v_lshl_add_u64 v[108:109], v[104:105], 0, s[98:99]
	global_load_dwordx4 v[224:227], v[38:39], off offset:16
	global_load_dwordx4 v[228:231], v[38:39], off
	global_load_dwordx4 v[232:235], v[106:107], off
	global_load_dwordx4 v[236:239], v[108:109], off
	global_load_dwordx4 v[144:147], v[106:107], off offset:16
	global_load_dwordx4 v[148:151], v[108:109], off offset:16
	global_load_dwordx4 v[152:155], v[40:41], off offset:16
	global_load_dwordx4 v[156:159], v[40:41], off
	global_load_dwordx4 v[160:163], v[106:107], off offset:2048
	global_load_dwordx4 v[164:167], v[108:109], off offset:2048
	global_load_dwordx4 v[168:171], v[106:107], off offset:2064
	global_load_dwordx4 v[172:175], v[108:109], off offset:2064
	v_pk_mul_f32 v[30:31], v[30:31], v[52:53] op_sel_hi:[1,0]
	v_pk_mul_f32 v[28:29], v[28:29], v[52:53] op_sel_hi:[1,0]
	s_waitcnt vmcnt(0)
	v_pk_mul_f32 v[30:31], v[74:75], v[30:31]
	v_pk_mul_f32 v[28:29], v[72:73], v[28:29]
	v_pk_mul_f32 v[26:27], v[26:27], v[52:53] op_sel_hi:[1,0]
	v_pk_mul_f32 v[24:25], v[24:25], v[52:53] op_sel_hi:[1,0]
	v_pk_mul_f32 v[26:27], v[70:71], v[26:27]
	v_pk_mul_f32 v[24:25], v[68:69], v[24:25]
	s_mov_b32 s30, 0xc944000
	v_pk_mul_f32 v[18:19], v[18:19], v[52:53] op_sel_hi:[1,0]
	v_pk_mul_f32 v[16:17], v[16:17], v[52:53] op_sel_hi:[1,0]
	v_pk_mul_f32 v[22:23], v[22:23], v[52:53] op_sel_hi:[1,0]
	v_pk_mul_f32 v[20:21], v[20:21], v[52:53] op_sel_hi:[1,0]
	s_waitcnt lgkmcnt(0)
	v_pk_add_f32 v[60:61], v[78:79], 1.0 op_sel_hi:[1,0]
	v_pk_add_f32 v[72:73], v[76:77], 1.0 op_sel_hi:[1,0]
	v_pk_fma_f32 v[60:61], v[60:61], v[30:31], v[82:83]
	v_pk_fma_f32 v[76:77], v[72:73], v[28:29], v[80:81]
	s_nop 1
	v_mov_b64_e32 v[28:29], v[112:113]
	v_mov_b64_e32 v[30:31], v[114:115]
	s_nop 1
	v_mov_b64_e32 v[72:73], v[116:117]
	v_mov_b64_e32 v[74:75], v[118:119]
	s_waitcnt vmcnt(0) lgkmcnt(0)
	v_pk_add_f32 v[30:31], v[30:31], 1.0 op_sel_hi:[1,0]
	v_pk_add_f32 v[28:29], v[28:29], 1.0 op_sel_hi:[1,0]
	v_pk_fma_f32 v[30:31], v[30:31], v[26:27], v[74:75]
	v_pk_fma_f32 v[26:27], v[28:29], v[24:25], v[72:73]
	v_lshl_add_u64 v[28:29], v[48:49], 0, v[44:45]
	v_add_co_u32_e32 v28, vcc, s30, v28
	v_cvt_pk_bf16_f32 v24, v76, v77
	v_cvt_pk_bf16_f32 v25, v60, v61
	v_cvt_pk_bf16_f32 v26, v26, v27
	v_cvt_pk_bf16_f32 v27, v30, v31
	v_addc_co_u32_e32 v29, vcc, 0, v29, vcc
	flat_store_dwordx4 v[28:29], v[24:27]
	s_nop 1
	v_mov_b64_e32 v[24:25], v[120:121]
	v_mov_b64_e32 v[26:27], v[122:123]
	s_nop 0
	s_nop 1
	v_mov_b64_e32 v[68:69], v[124:125]
	v_mov_b64_e32 v[70:71], v[126:127]
	s_nop 1
	v_mov_b64_e32 v[72:73], v[128:129]
	v_mov_b64_e32 v[74:75], v[130:131]
	s_nop 1
	v_mov_b64_e32 v[76:77], v[132:133]
	v_mov_b64_e32 v[78:79], v[134:135]
	s_mov_b32 s30, 0x8800
	v_cmp_gt_i32_e32 vcc, s30, v33
	s_waitcnt vmcnt(0)
	v_pk_mul_f32 v[20:21], v[24:25], v[20:21]
	v_pk_mul_f32 v[16:17], v[68:69], v[16:17]
	v_pk_mul_f32 v[18:19], v[70:71], v[18:19]
	s_waitcnt lgkmcnt(0)
	v_pk_add_f32 v[30:31], v[74:75], 1.0 op_sel_hi:[1,0]
	v_pk_add_f32 v[60:61], v[72:73], 1.0 op_sel_hi:[1,0]
	v_pk_fma_f32 v[30:31], v[30:31], v[18:19], v[78:79]
	v_pk_fma_f32 v[60:61], v[60:61], v[16:17], v[76:77]
	s_nop 1
	v_mov_b64_e32 v[16:17], v[136:137]
	v_mov_b64_e32 v[18:19], v[138:139]
	s_nop 0
	s_nop 1
	v_mov_b64_e32 v[54:55], v[140:141]
	v_mov_b64_e32 v[56:57], v[142:143]
	v_pk_mul_f32 v[22:23], v[26:27], v[22:23]
	s_waitcnt vmcnt(0) lgkmcnt(0)
	v_pk_add_f32 v[18:19], v[18:19], 1.0 op_sel_hi:[1,0]
	v_pk_add_f32 v[16:17], v[16:17], 1.0 op_sel_hi:[1,0]
	v_pk_fma_f32 v[22:23], v[22:23], v[18:19], v[56:57]
	v_pk_fma_f32 v[18:19], v[20:21], v[16:17], v[54:55]
	v_cvt_pk_bf16_f32 v16, v60, v61
	v_cvt_pk_bf16_f32 v17, v30, v31
	v_cvt_pk_bf16_f32 v18, v18, v19
	v_cvt_pk_bf16_f32 v19, v22, v23
	flat_store_dwordx4 v[28:29], v[16:19] offset:1024
	s_and_saveexec_b64 s[44:45], vcc
	s_cbranch_execz .LBB0_974
	v_min_i32_e32 v16, 0x8000, v33
	v_ashrrev_i32_e32 v16, 12, v16
	v_mul_i32_i24_e32 v16, 9, v16
	v_add_f32_e32 v20, v53, v58
	v_ashrrev_i32_e32 v17, 31, v16
	v_lshlrev_b64 v[18:19], 12, v[16:17]
	v_fmamk_f32 v16, v20, 0x3a800000, v191
	s_mov_b32 s30, 0x800000
	v_cmp_gt_f32_e32 vcc, s30, v16
	v_mul_f32_e32 v17, 0x4b800000, v16
	v_lshl_add_u64 v[30:31], v[42:43], 0, v[18:19]
	v_cndmask_b32_e32 v16, v16, v17, vcc
	v_rsq_f32_e32 v16, v16
	s_movk_i32 s30, 0x4000
	s_mov_b64 s[42:43], 0x4000
	v_lshl_add_u64 v[20:21], v[30:31], 0, s[42:43]
	v_mul_f32_e32 v17, 0x45800000, v16
	v_cndmask_b32_e32 v16, v16, v17, vcc
	v_add_co_u32_e32 v52, vcc, s30, v30
	s_mov_b64 s[42:43], 0x3000
	s_nop 0
	v_addc_co_u32_e32 v53, vcc, 0, v31, vcc
	s_movk_i32 s30, 0x3000
	v_lshl_add_u64 v[18:19], v[30:31], 0, s[42:43]
	v_add_co_u32_e32 v30, vcc, s30, v30
	v_mov_b64_e32 v[22:23], v[224:225]
	v_mov_b64_e32 v[24:25], v[226:227]
	v_mov_b64_e32 v[26:27], v[228:229]
	v_mov_b64_e32 v[28:29], v[230:231]
	v_addc_co_u32_e32 v31, vcc, 0, v31, vcc
	v_mov_b64_e32 v[52:53], v[232:233]
	v_mov_b64_e32 v[54:55], v[234:235]
	v_pk_mul_f32 v[14:15], v[14:15], v[16:17] op_sel_hi:[1,0]
	v_mov_b64_e32 v[56:57], v[236:237]
	v_mov_b64_e32 v[58:59], v[238:239]
	v_pk_mul_f32 v[12:13], v[12:13], v[16:17] op_sel_hi:[1,0]
	v_pk_mul_f32 v[10:11], v[10:11], v[16:17] op_sel_hi:[1,0]
	v_pk_mul_f32 v[8:9], v[8:9], v[16:17] op_sel_hi:[1,0]
	s_mov_b32 s30, 0xc944000
	v_pk_mul_f32 v[2:3], v[2:3], v[16:17] op_sel_hi:[1,0]
	v_pk_mul_f32 v[0:1], v[0:1], v[16:17] op_sel_hi:[1,0]
	v_pk_mul_f32 v[6:7], v[6:7], v[16:17] op_sel_hi:[1,0]
	v_pk_mul_f32 v[4:5], v[4:5], v[16:17] op_sel_hi:[1,0]
	s_waitcnt vmcnt(0)
	v_pk_mul_f32 v[8:9], v[8:9], v[22:23]
	v_pk_mul_f32 v[12:13], v[12:13], v[26:27]
	v_pk_mul_f32 v[14:15], v[14:15], v[28:29]
	v_pk_mul_f32 v[10:11], v[10:11], v[24:25]
	s_waitcnt lgkmcnt(0)
	v_pk_add_f32 v[26:27], v[54:55], 1.0 op_sel_hi:[1,0]
	v_pk_add_f32 v[28:29], v[52:53], 1.0 op_sel_hi:[1,0]
	v_pk_fma_f32 v[30:31], v[14:15], v[26:27], v[58:59]
	v_pk_fma_f32 v[52:53], v[12:13], v[28:29], v[56:57]
	s_nop 1
	v_mov_b64_e32 v[12:13], v[144:145]
	v_mov_b64_e32 v[14:15], v[146:147]
	s_nop 1
	v_mov_b64_e32 v[26:27], v[148:149]
	v_mov_b64_e32 v[28:29], v[150:151]
	s_waitcnt vmcnt(0) lgkmcnt(0)
	v_pk_add_f32 v[14:15], v[14:15], 1.0 op_sel_hi:[1,0]
	v_pk_add_f32 v[12:13], v[12:13], 1.0 op_sel_hi:[1,0]
	v_pk_fma_f32 v[14:15], v[10:11], v[14:15], v[28:29]
	v_pk_fma_f32 v[10:11], v[8:9], v[12:13], v[26:27]
	v_lshl_add_u64 v[12:13], v[46:47], 0, v[44:45]
	v_cvt_pk_bf16_f32 v9, v30, v31
	v_add_co_u32_e32 v30, vcc, s30, v12
	v_cvt_pk_bf16_f32 v8, v52, v53
	v_cvt_pk_bf16_f32 v10, v10, v11
	v_cvt_pk_bf16_f32 v11, v14, v15
	v_addc_co_u32_e32 v31, vcc, 0, v13, vcc
	flat_store_dwordx4 v[30:31], v[8:11]
	s_nop 1
	v_mov_b64_e32 v[8:9], v[152:153]
	v_mov_b64_e32 v[10:11], v[154:155]
	s_nop 0
	s_nop 1
	v_mov_b64_e32 v[12:13], v[156:157]
	v_mov_b64_e32 v[14:15], v[158:159]
	s_nop 1
	v_mov_b64_e32 v[22:23], v[160:161]
	v_mov_b64_e32 v[24:25], v[162:163]
	s_nop 1
	v_mov_b64_e32 v[26:27], v[164:165]
	v_mov_b64_e32 v[28:29], v[166:167]
	s_waitcnt vmcnt(0)
	v_pk_mul_f32 v[4:5], v[4:5], v[8:9]
	v_pk_mul_f32 v[0:1], v[0:1], v[12:13]
	v_pk_mul_f32 v[2:3], v[2:3], v[14:15]
	s_waitcnt lgkmcnt(0)
	v_pk_add_f32 v[12:13], v[24:25], 1.0 op_sel_hi:[1,0]
	v_pk_add_f32 v[14:15], v[22:23], 1.0 op_sel_hi:[1,0]
	v_pk_fma_f32 v[22:23], v[2:3], v[12:13], v[28:29]
	v_pk_fma_f32 v[24:25], v[0:1], v[14:15], v[26:27]
	s_nop 1
	v_mov_b64_e32 v[0:1], v[168:169]
	v_mov_b64_e32 v[2:3], v[170:171]
	s_nop 1
	v_mov_b64_e32 v[12:13], v[172:173]
	v_mov_b64_e32 v[14:15], v[174:175]
	v_pk_mul_f32 v[6:7], v[6:7], v[10:11]
	s_waitcnt vmcnt(0) lgkmcnt(0)
	v_pk_add_f32 v[2:3], v[2:3], 1.0 op_sel_hi:[1,0]
	v_pk_add_f32 v[0:1], v[0:1], 1.0 op_sel_hi:[1,0]
	v_pk_fma_f32 v[6:7], v[6:7], v[2:3], v[14:15]
	v_pk_fma_f32 v[2:3], v[4:5], v[0:1], v[12:13]
	v_cvt_pk_bf16_f32 v0, v24, v25
	v_cvt_pk_bf16_f32 v1, v22, v23
	v_cvt_pk_bf16_f32 v2, v2, v3
	v_cvt_pk_bf16_f32 v3, v6, v7
	flat_store_dwordx4 v[30:31], v[0:3] offset:1024
	s_branch .LBB0_974

.LBB0_2542:
	s_or_b64 exec, exec, s[50:51]
	s_waitcnt vmcnt(0) lgkmcnt(0)
	v_mul_f32_e32 v52, v29, v29
	v_mul_f32_e32 v53, v25, v25
	v_fmac_f32_e32 v52, v28, v28
	v_fmac_f32_e32 v53, v24, v24
	v_fmac_f32_e32 v52, v30, v30
	v_fmac_f32_e32 v53, v26, v26
	v_fmac_f32_e32 v52, v31, v31
	v_fmac_f32_e32 v53, v27, v27
	v_add_f32_e32 v52, v53, v52
	v_mul_f32_e32 v53, v17, v17
	v_fmac_f32_e32 v53, v16, v16
	v_fmac_f32_e32 v53, v18, v18
	v_fmac_f32_e32 v53, v19, v19
	v_add_f32_e32 v52, v53, v52
	v_mul_f32_e32 v53, v21, v21
	v_fmac_f32_e32 v53, v20, v20
	v_fmac_f32_e32 v53, v22, v22
	v_fmac_f32_e32 v53, v23, v23
	v_add_f32_e32 v52, v53, v52
	v_mul_f32_e32 v53, v13, v13
	v_mul_f32_e32 v54, v9, v9
	v_fmac_f32_e32 v53, v12, v12
	v_fmac_f32_e32 v54, v8, v8
	v_fmac_f32_e32 v53, v14, v14
	v_fmac_f32_e32 v54, v10, v10
	v_fmac_f32_e32 v53, v15, v15
	v_fmac_f32_e32 v54, v11, v11
	v_add_f32_e32 v53, v54, v53
	v_mul_f32_e32 v54, v1, v1
	v_fmac_f32_e32 v54, v0, v0
	v_fmac_f32_e32 v54, v2, v2
	v_fmac_f32_e32 v54, v3, v3
	v_add_f32_e32 v53, v54, v53
	v_mul_f32_e32 v54, v5, v5
	v_fmac_f32_e32 v54, v4, v4
	v_fmac_f32_e32 v54, v6, v6
	v_fmac_f32_e32 v54, v7, v7
	v_add_f32_e32 v53, v54, v53
	ds_bpermute_b32 v54, v35, v52
	s_mov_b32 s30, 0x800000
	s_mov_b64 s[40:41], 0x7000
	global_load_dwordx4 v[68:71], v[38:39], off offset:16
	global_load_dwordx4 v[72:75], v[38:39], off
	s_waitcnt lgkmcnt(0)
	v_add_f32_e32 v52, v52, v54
	ds_bpermute_b32 v54, v35, v53
	s_waitcnt lgkmcnt(0)
	v_add_f32_e32 v53, v53, v54
	ds_bpermute_b32 v54, v62, v52
	s_waitcnt lgkmcnt(0)
	v_add_f32_e32 v52, v52, v54
	ds_bpermute_b32 v54, v62, v53
	s_waitcnt lgkmcnt(0)
	v_add_f32_e32 v53, v53, v54
	ds_bpermute_b32 v54, v63, v52
	s_waitcnt lgkmcnt(0)
	v_add_f32_e32 v52, v52, v54
	ds_bpermute_b32 v54, v63, v53
	s_waitcnt lgkmcnt(0)
	v_add_f32_e32 v53, v53, v54
	ds_bpermute_b32 v54, v64, v52
	s_waitcnt lgkmcnt(0)
	v_add_f32_e32 v52, v52, v54
	ds_bpermute_b32 v54, v64, v53
	s_waitcnt lgkmcnt(0)
	v_add_f32_e32 v53, v53, v54
	ds_bpermute_b32 v54, v65, v52
	s_waitcnt lgkmcnt(0)
	v_add_f32_e32 v52, v52, v54
	ds_bpermute_b32 v54, v65, v53
	s_waitcnt lgkmcnt(0)
	v_add_f32_e32 v53, v53, v54
	ds_bpermute_b32 v54, v66, v52
	ds_bpermute_b32 v58, v66, v53
	s_waitcnt lgkmcnt(1)
	v_add_f32_e32 v52, v52, v54
	v_fmamk_f32 v52, v52, 0x3a800000, v191
	v_cmp_gt_f32_e32 vcc, s30, v52
	v_mul_f32_e32 v56, 0x4b800000, v52
	v_min_i32_e32 v54, 0x8000, v32
	v_cndmask_b32_e32 v52, v52, v56, vcc
	v_ashrrev_i32_e32 v54, 12, v54
	v_rsq_f32_e32 v52, v52
	v_mul_i32_i24_e32 v54, 9, v54
	v_ashrrev_i32_e32 v55, 31, v54
	v_lshlrev_b64 v[54:55], 12, v[54:55]
	v_mul_f32_e32 v56, 0x45800000, v52
	v_lshl_add_u64 v[60:61], v[42:43], 0, v[54:55]
	s_movk_i32 s30, 0x7000
	v_cndmask_b32_e32 v52, v52, v56, vcc
	v_add_co_u32_e32 v76, vcc, s30, v60
	v_lshl_add_u64 v[56:57], v[60:61], 0, s[40:41]
	s_mov_b64 s[40:41], 0x6000
	v_addc_co_u32_e32 v77, vcc, 0, v61, vcc
	s_movk_i32 s30, 0x6000
	v_lshl_add_u64 v[54:55], v[60:61], 0, s[40:41]
	v_add_co_u32_e32 v60, vcc, s30, v60
	flat_load_dwordx4 v[76:79], v[76:77]
	s_nop 0
	v_addc_co_u32_e32 v61, vcc, 0, v61, vcc
	flat_load_dwordx4 v[80:83], v[60:61]
	global_load_dwordx4 v[112:115], v[56:57], off offset:16
	global_load_dwordx4 v[116:119], v[54:55], off offset:16
	global_load_dwordx4 v[120:123], v[40:41], off offset:16
	global_load_dwordx4 v[124:127], v[40:41], off
	global_load_dwordx4 v[128:131], v[56:57], off offset:2048
	global_load_dwordx4 v[132:135], v[54:55], off offset:2048
	global_load_dwordx4 v[136:139], v[56:57], off offset:2064
	global_load_dwordx4 v[140:143], v[54:55], off offset:2064
	v_min_i32_e32 v104, 0x8000, v33
	v_ashrrev_i32_e32 v104, 12, v104
	v_mul_i32_i24_e32 v104, 9, v104
	v_ashrrev_i32_e32 v105, 31, v104
	v_lshlrev_b64 v[104:105], 12, v[104:105]
	v_lshl_add_u64 v[104:105], v[42:43], 0, v[104:105]
	s_mov_b64 s[98:99], 0x7000
	v_lshl_add_u64 v[106:107], v[104:105], 0, s[98:99]
	s_mov_b64 s[98:99], 0x6000
	v_lshl_add_u64 v[108:109], v[104:105], 0, s[98:99]
	global_load_dwordx4 v[224:227], v[38:39], off offset:16
	global_load_dwordx4 v[228:231], v[38:39], off
	global_load_dwordx4 v[232:235], v[106:107], off
	global_load_dwordx4 v[236:239], v[108:109], off
	global_load_dwordx4 v[144:147], v[106:107], off offset:16
	global_load_dwordx4 v[148:151], v[108:109], off offset:16
	global_load_dwordx4 v[152:155], v[40:41], off offset:16
	global_load_dwordx4 v[156:159], v[40:41], off
	global_load_dwordx4 v[160:163], v[106:107], off offset:2048
	global_load_dwordx4 v[164:167], v[108:109], off offset:2048
	global_load_dwordx4 v[168:171], v[106:107], off offset:2064
	global_load_dwordx4 v[172:175], v[108:109], off offset:2064
	v_pk_mul_f32 v[30:31], v[30:31], v[52:53] op_sel_hi:[1,0]
	v_pk_mul_f32 v[28:29], v[28:29], v[52:53] op_sel_hi:[1,0]
	s_waitcnt vmcnt(0)
	v_pk_mul_f32 v[30:31], v[74:75], v[30:31]
	v_pk_mul_f32 v[28:29], v[72:73], v[28:29]
	v_pk_mul_f32 v[26:27], v[26:27], v[52:53] op_sel_hi:[1,0]
	v_pk_mul_f32 v[24:25], v[24:25], v[52:53] op_sel_hi:[1,0]
	v_pk_mul_f32 v[26:27], v[70:71], v[26:27]
	v_pk_mul_f32 v[24:25], v[68:69], v[24:25]
	s_mov_b32 s30, 0xc944000
	v_pk_mul_f32 v[18:19], v[18:19], v[52:53] op_sel_hi:[1,0]
	v_pk_mul_f32 v[16:17], v[16:17], v[52:53] op_sel_hi:[1,0]
	v_pk_mul_f32 v[22:23], v[22:23], v[52:53] op_sel_hi:[1,0]
	v_pk_mul_f32 v[20:21], v[20:21], v[52:53] op_sel_hi:[1,0]
	s_waitcnt lgkmcnt(0)
	v_pk_add_f32 v[60:61], v[78:79], 1.0 op_sel_hi:[1,0]
	v_pk_add_f32 v[72:73], v[76:77], 1.0 op_sel_hi:[1,0]
	v_pk_fma_f32 v[60:61], v[60:61], v[30:31], v[82:83]
	v_pk_fma_f32 v[76:77], v[72:73], v[28:29], v[80:81]
	s_nop 1
	v_mov_b64_e32 v[28:29], v[112:113]
	v_mov_b64_e32 v[30:31], v[114:115]
	s_nop 1
	v_mov_b64_e32 v[72:73], v[116:117]
	v_mov_b64_e32 v[74:75], v[118:119]
	s_waitcnt vmcnt(0) lgkmcnt(0)
	v_pk_add_f32 v[30:31], v[30:31], 1.0 op_sel_hi:[1,0]
	v_pk_add_f32 v[28:29], v[28:29], 1.0 op_sel_hi:[1,0]
	v_pk_fma_f32 v[30:31], v[30:31], v[26:27], v[74:75]
	v_pk_fma_f32 v[26:27], v[28:29], v[24:25], v[72:73]
	v_lshl_add_u64 v[28:29], v[48:49], 0, v[44:45]
	v_add_co_u32_e32 v28, vcc, s30, v28
	v_cvt_pk_bf16_f32 v24, v76, v77
	v_cvt_pk_bf16_f32 v25, v60, v61
	v_cvt_pk_bf16_f32 v26, v26, v27
	v_cvt_pk_bf16_f32 v27, v30, v31
	v_addc_co_u32_e32 v29, vcc, 0, v29, vcc
	flat_store_dwordx4 v[28:29], v[24:27]
	s_nop 1
	v_mov_b64_e32 v[24:25], v[120:121]
	v_mov_b64_e32 v[26:27], v[122:123]
	s_nop 0
	s_nop 1
	v_mov_b64_e32 v[68:69], v[124:125]
	v_mov_b64_e32 v[70:71], v[126:127]
	s_nop 1
	v_mov_b64_e32 v[72:73], v[128:129]
	v_mov_b64_e32 v[74:75], v[130:131]
	s_nop 1
	v_mov_b64_e32 v[76:77], v[132:133]
	v_mov_b64_e32 v[78:79], v[134:135]
	s_mov_b32 s30, 0x8800
	v_cmp_gt_i32_e32 vcc, s30, v33
	s_waitcnt vmcnt(0)
	v_pk_mul_f32 v[20:21], v[24:25], v[20:21]
	v_pk_mul_f32 v[16:17], v[68:69], v[16:17]
	v_pk_mul_f32 v[18:19], v[70:71], v[18:19]
	s_waitcnt lgkmcnt(0)
	v_pk_add_f32 v[30:31], v[74:75], 1.0 op_sel_hi:[1,0]
	v_pk_add_f32 v[60:61], v[72:73], 1.0 op_sel_hi:[1,0]
	v_pk_fma_f32 v[30:31], v[30:31], v[18:19], v[78:79]
	v_pk_fma_f32 v[60:61], v[60:61], v[16:17], v[76:77]
	s_nop 1
	v_mov_b64_e32 v[16:17], v[136:137]
	v_mov_b64_e32 v[18:19], v[138:139]
	s_nop 0
	s_nop 1
	v_mov_b64_e32 v[54:55], v[140:141]
	v_mov_b64_e32 v[56:57], v[142:143]
	v_pk_mul_f32 v[22:23], v[26:27], v[22:23]
	s_waitcnt vmcnt(0) lgkmcnt(0)
	v_pk_add_f32 v[18:19], v[18:19], 1.0 op_sel_hi:[1,0]
	v_pk_add_f32 v[16:17], v[16:17], 1.0 op_sel_hi:[1,0]
	v_pk_fma_f32 v[22:23], v[22:23], v[18:19], v[56:57]
	v_pk_fma_f32 v[18:19], v[20:21], v[16:17], v[54:55]
	v_cvt_pk_bf16_f32 v16, v60, v61
	v_cvt_pk_bf16_f32 v17, v30, v31
	v_cvt_pk_bf16_f32 v18, v18, v19
	v_cvt_pk_bf16_f32 v19, v22, v23
	flat_store_dwordx4 v[28:29], v[16:19] offset:1024
	s_and_saveexec_b64 s[50:51], vcc
	s_cbranch_execz .LBB0_2537
	v_min_i32_e32 v16, 0x8000, v33
	v_ashrrev_i32_e32 v16, 12, v16
	v_mul_i32_i24_e32 v16, 9, v16
	v_add_f32_e32 v20, v53, v58
	v_ashrrev_i32_e32 v17, 31, v16
	v_lshlrev_b64 v[18:19], 12, v[16:17]
	v_fmamk_f32 v16, v20, 0x3a800000, v191
	s_mov_b32 s30, 0x800000
	v_cmp_gt_f32_e32 vcc, s30, v16
	v_mul_f32_e32 v17, 0x4b800000, v16
	v_lshl_add_u64 v[30:31], v[42:43], 0, v[18:19]
	v_cndmask_b32_e32 v16, v16, v17, vcc
	v_rsq_f32_e32 v16, v16
	s_movk_i32 s30, 0x7000
	s_mov_b64 s[40:41], 0x7000
	v_lshl_add_u64 v[20:21], v[30:31], 0, s[40:41]
	v_mul_f32_e32 v17, 0x45800000, v16
	v_cndmask_b32_e32 v16, v16, v17, vcc
	v_add_co_u32_e32 v52, vcc, s30, v30
	s_mov_b64 s[40:41], 0x6000
	s_nop 0
	v_addc_co_u32_e32 v53, vcc, 0, v31, vcc
	s_movk_i32 s30, 0x6000
	v_lshl_add_u64 v[18:19], v[30:31], 0, s[40:41]
	v_add_co_u32_e32 v30, vcc, s30, v30
	v_mov_b64_e32 v[22:23], v[224:225]
	v_mov_b64_e32 v[24:25], v[226:227]
	v_mov_b64_e32 v[26:27], v[228:229]
	v_mov_b64_e32 v[28:29], v[230:231]
	v_addc_co_u32_e32 v31, vcc, 0, v31, vcc
	v_mov_b64_e32 v[52:53], v[232:233]
	v_mov_b64_e32 v[54:55], v[234:235]
	v_pk_mul_f32 v[14:15], v[14:15], v[16:17] op_sel_hi:[1,0]
	v_mov_b64_e32 v[56:57], v[236:237]
	v_mov_b64_e32 v[58:59], v[238:239]
	v_pk_mul_f32 v[12:13], v[12:13], v[16:17] op_sel_hi:[1,0]
	v_pk_mul_f32 v[10:11], v[10:11], v[16:17] op_sel_hi:[1,0]
	v_pk_mul_f32 v[8:9], v[8:9], v[16:17] op_sel_hi:[1,0]
	s_mov_b32 s30, 0xc944000
	v_pk_mul_f32 v[2:3], v[2:3], v[16:17] op_sel_hi:[1,0]
	v_pk_mul_f32 v[0:1], v[0:1], v[16:17] op_sel_hi:[1,0]
	v_pk_mul_f32 v[6:7], v[6:7], v[16:17] op_sel_hi:[1,0]
	v_pk_mul_f32 v[4:5], v[4:5], v[16:17] op_sel_hi:[1,0]
	s_waitcnt vmcnt(0)
	v_pk_mul_f32 v[8:9], v[8:9], v[22:23]
	v_pk_mul_f32 v[12:13], v[12:13], v[26:27]
	v_pk_mul_f32 v[14:15], v[14:15], v[28:29]
	v_pk_mul_f32 v[10:11], v[10:11], v[24:25]
	s_waitcnt lgkmcnt(0)
	v_pk_add_f32 v[26:27], v[54:55], 1.0 op_sel_hi:[1,0]
	v_pk_add_f32 v[28:29], v[52:53], 1.0 op_sel_hi:[1,0]
	v_pk_fma_f32 v[30:31], v[14:15], v[26:27], v[58:59]
	v_pk_fma_f32 v[52:53], v[12:13], v[28:29], v[56:57]
	s_nop 1
	v_mov_b64_e32 v[12:13], v[144:145]
	v_mov_b64_e32 v[14:15], v[146:147]
	s_nop 1
	v_mov_b64_e32 v[26:27], v[148:149]
	v_mov_b64_e32 v[28:29], v[150:151]
	s_waitcnt vmcnt(0) lgkmcnt(0)
	v_pk_add_f32 v[14:15], v[14:15], 1.0 op_sel_hi:[1,0]
	v_pk_add_f32 v[12:13], v[12:13], 1.0 op_sel_hi:[1,0]
	v_pk_fma_f32 v[14:15], v[10:11], v[14:15], v[28:29]
	v_pk_fma_f32 v[10:11], v[8:9], v[12:13], v[26:27]
	v_lshl_add_u64 v[12:13], v[46:47], 0, v[44:45]
	v_cvt_pk_bf16_f32 v9, v30, v31
	v_add_co_u32_e32 v30, vcc, s30, v12
	v_cvt_pk_bf16_f32 v8, v52, v53
	v_cvt_pk_bf16_f32 v10, v10, v11
	v_cvt_pk_bf16_f32 v11, v14, v15
	v_addc_co_u32_e32 v31, vcc, 0, v13, vcc
	flat_store_dwordx4 v[30:31], v[8:11]
	s_nop 1
	v_mov_b64_e32 v[8:9], v[152:153]
	v_mov_b64_e32 v[10:11], v[154:155]
	s_nop 0
	s_nop 1
	v_mov_b64_e32 v[12:13], v[156:157]
	v_mov_b64_e32 v[14:15], v[158:159]
	s_nop 1
	v_mov_b64_e32 v[22:23], v[160:161]
	v_mov_b64_e32 v[24:25], v[162:163]
	s_nop 1
	v_mov_b64_e32 v[26:27], v[164:165]
	v_mov_b64_e32 v[28:29], v[166:167]
	s_waitcnt vmcnt(0)
	v_pk_mul_f32 v[4:5], v[4:5], v[8:9]
	v_pk_mul_f32 v[0:1], v[0:1], v[12:13]
	v_pk_mul_f32 v[2:3], v[2:3], v[14:15]
	s_waitcnt lgkmcnt(0)
	v_pk_add_f32 v[12:13], v[24:25], 1.0 op_sel_hi:[1,0]
	v_pk_add_f32 v[14:15], v[22:23], 1.0 op_sel_hi:[1,0]
	v_pk_fma_f32 v[22:23], v[2:3], v[12:13], v[28:29]
	v_pk_fma_f32 v[24:25], v[0:1], v[14:15], v[26:27]
	s_nop 1
	v_mov_b64_e32 v[0:1], v[168:169]
	v_mov_b64_e32 v[2:3], v[170:171]
	s_nop 1
	v_mov_b64_e32 v[12:13], v[172:173]
	v_mov_b64_e32 v[14:15], v[174:175]
	v_pk_mul_f32 v[6:7], v[6:7], v[10:11]
	s_waitcnt vmcnt(0) lgkmcnt(0)
	v_pk_add_f32 v[2:3], v[2:3], 1.0 op_sel_hi:[1,0]
	v_pk_add_f32 v[0:1], v[0:1], 1.0 op_sel_hi:[1,0]
	v_pk_fma_f32 v[6:7], v[6:7], v[2:3], v[14:15]
	v_pk_fma_f32 v[2:3], v[4:5], v[0:1], v[12:13]
	v_cvt_pk_bf16_f32 v0, v24, v25
	v_cvt_pk_bf16_f32 v1, v22, v23
	v_cvt_pk_bf16_f32 v2, v2, v3
	v_cvt_pk_bf16_f32 v3, v6, v7
	flat_store_dwordx4 v[30:31], v[0:3] offset:1024
	s_branch .LBB0_2537
